# v051 + P1 dt-weight LDS staging batched (4 loads, one wait) + P0 silu staging batched (16 loads via SGPR bases, one wait)
# speedup vs baseline: 1.0363x; 1.0094x over previous
.LBB0_18:
	s_mul_hi_i32 s6, s30, 0x2aaaaaab
	s_lshr_b32 s7, s6, 31
	s_ashr_i32 s31, s6, 3
	s_add_i32 s31, s31, s7
	s_lshl_b32 s33, s31, 3
	s_load_dwordx4 s[40:43], s[0:1], 0x10
	s_waitcnt lgkmcnt(0)
	s_add_i32 s34, s33, 0
	s_add_i32 s35, s34, -32
	s_cmp_gt_i32 s34, 31
	s_cselect_b32 s34, s35, s34
	s_cselect_b32 s36, s42, s40
	s_cselect_b32 s37, s43, s41
	s_lshl_b32 s34, s34, 12
	s_add_u32 s36, s36, s34
	s_addc_u32 s37, s37, 0
	global_load_dword v30, v25, s[36:37]
	global_load_dword v31, v25, s[36:37] offset:2048
	s_add_i32 s34, s33, 1
	s_add_i32 s35, s34, -32
	s_cmp_gt_i32 s34, 31
	s_cselect_b32 s34, s35, s34
	s_cselect_b32 s36, s42, s40
	s_cselect_b32 s37, s43, s41
	s_lshl_b32 s34, s34, 12
	s_add_u32 s36, s36, s34
	s_addc_u32 s37, s37, 0
	global_load_dword v32, v25, s[36:37]
	global_load_dword v33, v25, s[36:37] offset:2048
	s_add_i32 s34, s33, 2
	s_add_i32 s35, s34, -32
	s_cmp_gt_i32 s34, 31
	s_cselect_b32 s34, s35, s34
	s_cselect_b32 s36, s42, s40
	s_cselect_b32 s37, s43, s41
	s_lshl_b32 s34, s34, 12
	s_add_u32 s36, s36, s34
	s_addc_u32 s37, s37, 0
	global_load_dword v34, v25, s[36:37]
	global_load_dword v35, v25, s[36:37] offset:2048
	s_add_i32 s34, s33, 3
	s_add_i32 s35, s34, -32
	s_cmp_gt_i32 s34, 31
	s_cselect_b32 s34, s35, s34
	s_cselect_b32 s36, s42, s40
	s_cselect_b32 s37, s43, s41
	s_lshl_b32 s34, s34, 12
	s_add_u32 s36, s36, s34
	s_addc_u32 s37, s37, 0
	global_load_dword v36, v25, s[36:37]
	global_load_dword v37, v25, s[36:37] offset:2048
	s_add_i32 s34, s33, 4
	s_add_i32 s35, s34, -32
	s_cmp_gt_i32 s34, 31
	s_cselect_b32 s34, s35, s34
	s_cselect_b32 s36, s42, s40
	s_cselect_b32 s37, s43, s41
	s_lshl_b32 s34, s34, 12
	s_add_u32 s36, s36, s34
	s_addc_u32 s37, s37, 0
	global_load_dword v38, v25, s[36:37]
	global_load_dword v39, v25, s[36:37] offset:2048
	s_add_i32 s34, s33, 5
	s_add_i32 s35, s34, -32
	s_cmp_gt_i32 s34, 31
	s_cselect_b32 s34, s35, s34
	s_cselect_b32 s36, s42, s40
	s_cselect_b32 s37, s43, s41
	s_lshl_b32 s34, s34, 12
	s_add_u32 s36, s36, s34
	s_addc_u32 s37, s37, 0
	global_load_dword v40, v25, s[36:37]
	global_load_dword v41, v25, s[36:37] offset:2048
	s_add_i32 s34, s33, 6
	s_add_i32 s35, s34, -32
	s_cmp_gt_i32 s34, 31
	s_cselect_b32 s34, s35, s34
	s_cselect_b32 s36, s42, s40
	s_cselect_b32 s37, s43, s41
	s_lshl_b32 s34, s34, 12
	s_add_u32 s36, s36, s34
	s_addc_u32 s37, s37, 0
	global_load_dword v42, v25, s[36:37]
	global_load_dword v43, v25, s[36:37] offset:2048
	s_add_i32 s34, s33, 7
	s_add_i32 s35, s34, -32
	s_cmp_gt_i32 s34, 31
	s_cselect_b32 s34, s35, s34
	s_cselect_b32 s36, s42, s40
	s_cselect_b32 s37, s43, s41
	s_lshl_b32 s34, s34, 12
	s_add_u32 s36, s36, s34
	s_addc_u32 s37, s37, 0
	global_load_dword v44, v25, s[36:37]
	global_load_dword v45, v25, s[36:37] offset:2048
	s_waitcnt vmcnt(0)
	v_mul_f32_e32 v46, 0xbfb8aa3b, v30
	v_mul_f32_e32 v47, 0xbfb8aa3b, v31
	v_mul_f32_e32 v48, 0xbfb8aa3b, v32
	v_mul_f32_e32 v49, 0xbfb8aa3b, v33
	v_exp_f32_e32 v46, v46
	v_exp_f32_e32 v47, v47
	v_exp_f32_e32 v48, v48
	v_exp_f32_e32 v49, v49
	v_add_f32_e32 v46, 1.0, v46
	v_add_f32_e32 v47, 1.0, v47
	v_add_f32_e32 v48, 1.0, v48
	v_add_f32_e32 v49, 1.0, v49
	v_rcp_f32_e32 v46, v46
	v_rcp_f32_e32 v47, v47
	v_rcp_f32_e32 v48, v48
	v_rcp_f32_e32 v49, v49
	v_mul_f32_e32 v30, v30, v46
	v_mul_f32_e32 v31, v31, v47
	v_mul_f32_e32 v32, v32, v48
	v_mul_f32_e32 v33, v33, v49
	ds_write_b32 v25, v30
	ds_write_b32 v25, v31 offset:2048
	ds_write_b32 v25, v32 offset:4096
	ds_write_b32 v25, v33 offset:6144
	v_mul_f32_e32 v46, 0xbfb8aa3b, v34
	v_mul_f32_e32 v47, 0xbfb8aa3b, v35
	v_mul_f32_e32 v48, 0xbfb8aa3b, v36
	v_mul_f32_e32 v49, 0xbfb8aa3b, v37
	v_exp_f32_e32 v46, v46
	v_exp_f32_e32 v47, v47
	v_exp_f32_e32 v48, v48
	v_exp_f32_e32 v49, v49
	v_add_f32_e32 v46, 1.0, v46
	v_add_f32_e32 v47, 1.0, v47
	v_add_f32_e32 v48, 1.0, v48
	v_add_f32_e32 v49, 1.0, v49
	v_rcp_f32_e32 v46, v46
	v_rcp_f32_e32 v47, v47
	v_rcp_f32_e32 v48, v48
	v_rcp_f32_e32 v49, v49
	v_mul_f32_e32 v34, v34, v46
	v_mul_f32_e32 v35, v35, v47
	v_mul_f32_e32 v36, v36, v48
	v_mul_f32_e32 v37, v37, v49
	ds_write_b32 v25, v34 offset:8192
	ds_write_b32 v25, v35 offset:10240
	ds_write_b32 v25, v36 offset:12288
	ds_write_b32 v25, v37 offset:14336
	v_mul_f32_e32 v46, 0xbfb8aa3b, v38
	v_mul_f32_e32 v47, 0xbfb8aa3b, v39
	v_mul_f32_e32 v48, 0xbfb8aa3b, v40
	v_mul_f32_e32 v49, 0xbfb8aa3b, v41
	v_exp_f32_e32 v46, v46
	v_exp_f32_e32 v47, v47
	v_exp_f32_e32 v48, v48
	v_exp_f32_e32 v49, v49
	v_add_f32_e32 v46, 1.0, v46
	v_add_f32_e32 v47, 1.0, v47
	v_add_f32_e32 v48, 1.0, v48
	v_add_f32_e32 v49, 1.0, v49
	v_rcp_f32_e32 v46, v46
	v_rcp_f32_e32 v47, v47
	v_rcp_f32_e32 v48, v48
	v_rcp_f32_e32 v49, v49
	v_mul_f32_e32 v38, v38, v46
	v_mul_f32_e32 v39, v39, v47
	v_mul_f32_e32 v40, v40, v48
	v_mul_f32_e32 v41, v41, v49
	ds_write_b32 v25, v38 offset:16384
	ds_write_b32 v25, v39 offset:18432
	ds_write_b32 v25, v40 offset:20480
	ds_write_b32 v25, v41 offset:22528
	v_mul_f32_e32 v46, 0xbfb8aa3b, v42
	v_mul_f32_e32 v47, 0xbfb8aa3b, v43
	v_mul_f32_e32 v48, 0xbfb8aa3b, v44
	v_mul_f32_e32 v49, 0xbfb8aa3b, v45
	v_exp_f32_e32 v46, v46
	v_exp_f32_e32 v47, v47
	v_exp_f32_e32 v48, v48
	v_exp_f32_e32 v49, v49
	v_add_f32_e32 v46, 1.0, v46
	v_add_f32_e32 v47, 1.0, v47
	v_add_f32_e32 v48, 1.0, v48
	v_add_f32_e32 v49, 1.0, v49
	v_rcp_f32_e32 v46, v46
	v_rcp_f32_e32 v47, v47
	v_rcp_f32_e32 v48, v48
	v_rcp_f32_e32 v49, v49
	v_mul_f32_e32 v42, v42, v46
	v_mul_f32_e32 v43, v43, v47
	v_mul_f32_e32 v44, v44, v48
	v_mul_f32_e32 v45, v45, v49
	ds_write_b32 v25, v42 offset:24576
	ds_write_b32 v25, v43 offset:26624
	ds_write_b32 v25, v44 offset:28672
	ds_write_b32 v25, v45 offset:30720
	s_mul_i32 s6, s31, 48
	s_sub_i32 s6, s30, s6
	s_lshl_b32 s10, s6, 6
	s_ashr_i32 s11, s10, 31
	v_mov_b32_e32 v10, 0
	v_lshl_add_u64 v[8:9], s[10:11], 2, v[4:5]
	s_mov_b64 s[12:13], 0
	s_mov_b32 s33, s3
	v_mov_b32_e32 v11, v10
	v_mov_b32_e32 v12, v10
	v_mov_b32_e32 v13, v10
	v_mov_b32_e32 v14, v10
	v_mov_b32_e32 v15, v10
	v_mov_b32_e32 v16, v10
	v_mov_b32_e32 v17, v10
	s_waitcnt lgkmcnt(0)
	s_barrier

.LBB0_43:
	v_ashrrev_i32_e32 v26, 7, v21
	v_and_b32_e32 v27, 0x7f0, v17
	v_mul_lo_u32 v26, v26, s3
	v_add3_u32 v26, s14, v26, v27
	global_load_dwordx4 v[22:25], v[18:19], off
	v_lshl_add_u64 v[18:19], v[18:19], 0, s[12:13]
	global_load_dwordx4 v[28:31], v[18:19], off
	v_lshl_add_u64 v[18:19], v[18:19], 0, s[12:13]
	global_load_dwordx4 v[32:35], v[18:19], off
	v_lshl_add_u64 v[18:19], v[18:19], 0, s[12:13]
	global_load_dwordx4 v[36:39], v[18:19], off
	s_waitcnt vmcnt(0)
	ds_write_b128 v26, v[22:25]
	ds_write_b128 v26, v[28:31] offset:8256
	ds_write_b128 v26, v[32:35] offset:16512
	ds_write_b128 v26, v[36:39] offset:24768
